# gemm_qkv q-tile epilogue: rope cos/sin rows prefetched through a 5-deep register ring instead of a load-wait-store round trip per 16-row group
# baseline (speedup 1.0000x reference)
; DEVI uint32_t pk(float a, float b) { const hwf32x2 v = {a, b}; return __builtin_bit_cast(uint32_t, __builtin_convertvector(v, hwbf16x2)); }
;     ...
;         if (TRANS) Ct[(64 * wn + 32 * ni + ri) * CT_LD + 64 * wm + 32 * mi + lr] = acc[mi][ni][r];
;         else Ct[(64 * wm + 32 * mi + ri) * CT_LD + 64 * wn + 32 * ni + lr] = acc[mi][ni][r];
;       }
;   __syncthreads();
; __device__ void phase_gemm_qkv(const P& p, int vb, int nvb, char* smem) {
;     ...
;       int te = threadIdx.x; asm volatile("" : "+v"(te)); const int c8 = te & 15, tq = te >> 4;
;       const int gc = nt * 128 + c8 * 8; const int hd = gc / 96; const int d = gc - hd * 96;
; #pragma unroll
;       for (int i = 0; i < 8; i++) {
;         const int r = tq + 16 * i; const float s = rs[r]; const int prow = mt * 128 + r;
;         if (d < 64) {
;           const float4 v0 = *(const float4*)(Ct + r * CT_LD + c8 * 8), v1 = *(const float4*)(Ct + r * CT_LD + c8 * 8 + 4);
;           *(uint4*)(Q + (size_t)prow * 768 + gc) = make_uint4(pk(v0.x * s, v0.y * s), pk(v0.z * s, v0.w * s), pk(v1.x * s, v1.y * s), pk(v1.z * s, v1.w * s));
;         } else if (d < 80) {
;           const int pos = prow % TP; float o1[8], o2[8];
.LBB0_175:
	s_or_b64 exec, exec, s[0:1]
	v_lshl_or_b32 v64, v169, 2, v173
	s_waitcnt lgkmcnt(0)
	v_lshl_add_u32 v65, v167, 8, 16
	v_lshlrev_b32_e32 v66, 2, v168
	v_mul_lo_u32 v64, v64, s43
	v_add3_u32 v64, v65, v66, v64
	ds_write2_b32 v64, v32, v48 offset1:32
	ds_write2_b32 v64, v33, v49 offset0:132 offset1:164
	v_add_u32_e32 v32, 0x400, v64
	ds_write2_b32 v32, v34, v50 offset0:8 offset1:40
	ds_write2_b32 v32, v35, v51 offset0:140 offset1:172
	v_add_u32_e32 v32, 0x1000, v64
	ds_write2_b32 v32, v36, v52 offset0:32 offset1:64
	ds_write2_b32 v32, v37, v53 offset0:164 offset1:196
	v_add_u32_e32 v32, 0x1400, v64
	ds_write2_b32 v32, v38, v54 offset0:40 offset1:72
	ds_write2_b32 v32, v39, v55 offset0:172 offset1:204
	v_add_u32_e32 v32, 0x2000, v64
	ds_write2_b32 v32, v40, v56 offset0:64 offset1:96
	ds_write2_b32 v32, v41, v57 offset0:196 offset1:228
	v_add_u32_e32 v32, 0x2400, v64
	ds_write2_b32 v32, v42, v58 offset0:72 offset1:104
	ds_write2_b32 v32, v43, v59 offset0:204 offset1:236
	v_add_u32_e32 v32, 0x3000, v64
	ds_write2_b32 v32, v44, v60 offset0:96 offset1:128
	v_add_u32_e32 v32, 0x3200, v64
	ds_write2_b32 v32, v45, v61 offset0:100 offset1:132
	v_add_u32_e32 v32, 0x3400, v64
	ds_write2_b32 v32, v46, v62 offset0:104 offset1:136
	v_add_u32_e32 v32, 0x3600, v64
	ds_write2_b32 v32, v47, v63 offset0:108 offset1:140
	v_add_u32_e32 v32, 0x4000, v64
	ds_write2_b32 v32, v0, v16 offset0:128 offset1:160
	v_add_u32_e32 v0, 0x4400, v64
	ds_write2_b32 v0, v1, v17 offset0:4 offset1:36
	ds_write2_b32 v0, v2, v18 offset0:136 offset1:168
	v_add_u32_e32 v0, 0x4800, v64
	ds_write2_b32 v0, v3, v19 offset0:12 offset1:44
	v_add_u32_e32 v0, 0x5000, v64
	ds_write2_b32 v0, v4, v20 offset0:160 offset1:192
	v_add_u32_e32 v0, 0x5400, v64
	ds_write2_b32 v0, v5, v21 offset0:36 offset1:68
	ds_write2_b32 v0, v6, v22 offset0:168 offset1:200
	v_add_u32_e32 v0, 0x5800, v64
	ds_write2_b32 v0, v7, v23 offset0:44 offset1:76
	v_add_u32_e32 v0, 0x6000, v64
	ds_write2_b32 v0, v8, v24 offset0:192 offset1:224
	v_add_u32_e32 v0, 0x6400, v64
	ds_write2_b32 v0, v9, v25 offset0:68 offset1:100
	ds_write2_b32 v0, v10, v26 offset0:200 offset1:232
	v_add_u32_e32 v0, 0x6800, v64
	ds_write2_b32 v0, v11, v27 offset0:76 offset1:108
	v_add_u32_e32 v0, 0x7200, v64
	ds_write2_b32 v0, v12, v28 offset0:96 offset1:128
	v_add_u32_e32 v0, 0x7400, v64
	ds_write2_b32 v0, v13, v29 offset0:100 offset1:132
	v_add_u32_e32 v0, 0x7600, v64
	ds_write2_b32 v0, v14, v30 offset0:104 offset1:136
	v_add_u32_e32 v0, 0x7800, v64
	ds_write2_b32 v0, v15, v31 offset0:108 offset1:140
	v_mov_b32_e32 v0, v178
	s_waitcnt lgkmcnt(0)
	s_barrier
	s_mov_b32 s0, 0x2aaaaaab
	v_ashrrev_i32_e32 v12, 4, v0
	v_lshlrev_b32_e32 v0, 3, v0
	v_and_b32_e32 v1, 0x78, v0
	v_subrev_u32_e32 v0, s67, v1
	v_add_u32_e32 v0, s62, v0
	v_add_u32_e32 v0, 0x500, v0
	v_mul_hi_i32 v2, v0, s0
	v_lshrrev_b32_e32 v3, 31, v2
	v_lshrrev_b32_e32 v2, 4, v2
	v_add_u32_e32 v2, v2, v3
	s_movk_i32 s0, 0x60
	v_mul_lo_u32 v2, v2, s0
	v_sub_u32_e32 v3, v0, v2
	v_lshl_add_u32 v2, v1, 2, 16
	v_lshl_add_u32 v1, v12, 2, 16
	v_add_u32_e32 v13, 0x12000, v1
	ds_read_b32 v10, v13
	s_movk_i32 s0, 0x50
	v_ashrrev_i32_e32 v1, 31, v0
	v_cmp_lt_i32_e64 s[38:39], 63, v3
	v_cmp_gt_u32_e32 vcc, s0, v3
	v_subrev_u32_e32 v3, 64, v3
	v_lshl_add_u64 v[0:1], v[0:1], 1, s[44:45]
	v_add_u32_e32 v14, s26, v12
	s_and_saveexec_b64 s[0:1], s[38:39]
	s_xor_b64 s[0:1], exec, s[0:1]
	s_cbranch_execz .LBB0_179
	s_and_saveexec_b64 s[66:67], vcc
	s_cbranch_execz .LBB0_178
; DEVI uint32_t pk(float a, float b) { const hwf32x2 v = {a, b}; return __builtin_bit_cast(uint32_t, __builtin_convertvector(v, hwbf16x2)); }
; __device__ void phase_gemm_qkv(const P& p, int vb, int nvb, char* smem) {
;     ...
;         const int r = tq + 16 * i; const float s = rs[r]; const int prow = mt * 128 + r;
;         if (d < 64) {
;           const float4 v0 = *(const float4*)(Ct + r * CT_LD + c8 * 8), v1 = *(const float4*)(Ct + r * CT_LD + c8 * 8 + 4);
;           *(uint4*)(Q + (size_t)prow * 768 + gc) = make_uint4(pk(v0.x * s, v0.y * s), pk(v0.z * s, v0.w * s), pk(v1.x * s, v1.y * s), pk(v1.z * s, v1.w * s));
;         } else if (d < 80) {
;           const int pos = prow % TP; float o1[8], o2[8];
; #pragma unroll
;           for (int e = 0; e < 8; e++) {
;             const int c = c8 * 8 + e; const int j = d - 64 + e;
;             const float x1 = Ct[r * CT_LD + c] * s, x2 = Ct[r * CT_LD + c + 16] * s;
;             const float cs = cost[pos * 16 + j], sn = sint[pos * 16 + j];
;             o1[e] = x1 * cs - x2 * sn; o2[e] = x2 * cs + x1 * sn;
;           }
;           *(uint4*)(Q + (size_t)prow * 768 + gc) = make_uint4(pk(o1[0], o1[1]), pk(o1[2], o1[3]), pk(o1[4], o1[5]), pk(o1[6], o1[7]));
;           *(uint4*)(Q + (size_t)prow * 768 + gc + 16) = make_uint4(pk(o2[0], o2[1]), pk(o2[2], o2[3]), pk(o2[4], o2[5]), pk(o2[6], o2[7]));
	v_mul_hi_i32 v4, v14, s35
	v_lshrrev_b32_e32 v5, 31, v4
	v_ashrrev_i32_e32 v4, 10, v4
	v_add_u32_e32 v4, v4, v5
	v_mul_i32_i24_e32 v4, 0x1080, v4
	v_sub_u32_e32 v4, v14, v4
	v_lshl_add_u32 v4, v4, 4, v3
	v_ashrrev_i32_e32 v5, 31, v4
	v_lshlrev_b64 v[4:5], 2, v[4:5]
	v_mad_u64_u32 v[8:9], s[40:41], v12, s43, v[2:3]
	v_lshl_add_u64 v[20:21], s[68:69], 0, v[4:5]
	v_lshl_add_u64 v[36:37], s[28:29], 0, v[4:5]
	ds_read_b128 v[4:7], v8 offset:64
	v_mov_b32_e32 v42, v20
	v_mov_b32_e32 v43, v21
	v_mov_b32_e32 v44, v36
	v_mov_b32_e32 v45, v37
	s_mov_b64 s[98:99], 0x1000
	v_lshl_add_u64 v[46:47], v[20:21], 0, s[98:99]
	v_lshl_add_u64 v[48:49], v[36:37], 0, s[98:99]
	global_load_dwordx4 v[68:71], v[42:43], off offset:16
	global_load_dwordx4 v[64:67], v[42:43], off
	global_load_dwordx4 v[76:79], v[44:45], off offset:16
	global_load_dwordx4 v[72:75], v[44:45], off
	global_load_dwordx4 v[84:87], v[42:43], off offset:1040
	global_load_dwordx4 v[80:83], v[42:43], off offset:1024
	global_load_dwordx4 v[92:95], v[44:45], off offset:1040
	global_load_dwordx4 v[88:91], v[44:45], off offset:1024
	global_load_dwordx4 v[100:103], v[42:43], off offset:2064
	global_load_dwordx4 v[96:99], v[42:43], off offset:2048
	global_load_dwordx4 v[108:111], v[44:45], off offset:2064
	global_load_dwordx4 v[104:107], v[44:45], off offset:2048
	global_load_dwordx4 v[116:119], v[42:43], off offset:3088
	global_load_dwordx4 v[112:115], v[42:43], off offset:3072
	global_load_dwordx4 v[124:127], v[44:45], off offset:3088
	global_load_dwordx4 v[120:123], v[44:45], off offset:3072
	global_load_dwordx4 v[132:135], v[46:47], off offset:16
	global_load_dwordx4 v[128:131], v[46:47], off
	global_load_dwordx4 v[140:143], v[48:49], off offset:16
	global_load_dwordx4 v[136:139], v[48:49], off
	s_nop 0
	ds_read_b128 v[24:27], v8
	ds_read_b128 v[28:31], v8 offset:16
	s_nop 0
	v_mad_i64_i32 v[14:15], s[40:41], v14, s36, v[0:1]
	s_waitcnt lgkmcnt(2)
	v_pk_mul_f32 v[4:5], v[10:11], v[4:5] op_sel_hi:[0,1]
	s_waitcnt lgkmcnt(1)
	v_pk_mul_f32 v[24:25], v[10:11], v[24:25] op_sel_hi:[0,1]
	v_pk_mul_f32 v[6:7], v[10:11], v[6:7] op_sel_hi:[0,1]
	s_waitcnt vmcnt(16)
	v_mov_b32_e32 v20, v64
	v_mov_b32_e32 v21, v65
	v_mov_b32_e32 v22, v66
	v_mov_b32_e32 v23, v67
	v_mov_b32_e32 v16, v68
	v_mov_b32_e32 v17, v69
	v_mov_b32_e32 v18, v70
	v_mov_b32_e32 v19, v71
	v_mov_b32_e32 v36, v72
	v_mov_b32_e32 v37, v73
	v_mov_b32_e32 v38, v74
	v_mov_b32_e32 v39, v75
	v_mov_b32_e32 v32, v76
	v_mov_b32_e32 v33, v77
	v_mov_b32_e32 v34, v78
	v_mov_b32_e32 v35, v79
	v_pk_mul_f32 v[40:41], v[4:5], v[36:37]
	s_nop 0
	v_pk_fma_f32 v[40:41], v[24:25], v[20:21], v[40:41] neg_lo:[0,0,1] neg_hi:[0,0,1]
	v_pk_mul_f32 v[24:25], v[24:25], v[36:37]
	s_nop 0
	v_pk_fma_f32 v[4:5], v[4:5], v[20:21], v[24:25]
	v_pk_mul_f32 v[20:21], v[10:11], v[26:27] op_sel_hi:[0,1]
	v_pk_mul_f32 v[24:25], v[6:7], v[38:39]
	v_cvt_pk_bf16_f32 v4, v4, v5
	v_pk_fma_f32 v[24:25], v[20:21], v[22:23], v[24:25] neg_lo:[0,0,1] neg_hi:[0,0,1]
	v_pk_mul_f32 v[20:21], v[20:21], v[38:39]
	s_nop 0
	v_pk_fma_f32 v[6:7], v[6:7], v[22:23], v[20:21]
	ds_read_b128 v[20:23], v8 offset:80
	v_cvt_pk_bf16_f32 v5, v6, v7
	s_waitcnt lgkmcnt(0)
	v_pk_mul_f32 v[8:9], v[10:11], v[20:21] op_sel_hi:[0,1]
	v_pk_mul_f32 v[20:21], v[10:11], v[28:29] op_sel_hi:[0,1]
	v_pk_mul_f32 v[26:27], v[8:9], v[32:33]
	s_nop 0
	v_pk_fma_f32 v[26:27], v[20:21], v[16:17], v[26:27] neg_lo:[0,0,1] neg_hi:[0,0,1]
	v_pk_mul_f32 v[20:21], v[20:21], v[32:33]
	s_nop 0
	v_pk_fma_f32 v[8:9], v[8:9], v[16:17], v[20:21]
	v_pk_mul_f32 v[16:17], v[10:11], v[22:23] op_sel_hi:[0,1]
	v_pk_mul_f32 v[10:11], v[10:11], v[30:31] op_sel_hi:[0,1]
	v_pk_mul_f32 v[20:21], v[16:17], v[34:35]
	v_cvt_pk_bf16_f32 v6, v8, v9
	v_pk_fma_f32 v[20:21], v[10:11], v[18:19], v[20:21] neg_lo:[0,0,1] neg_hi:[0,0,1]
	v_pk_mul_f32 v[10:11], v[10:11], v[34:35]
	s_nop 0
	v_pk_fma_f32 v[10:11], v[16:17], v[18:19], v[10:11]
	v_cvt_pk_bf16_f32 v16, v40, v41
	v_cvt_pk_bf16_f32 v17, v24, v25
	v_cvt_pk_bf16_f32 v18, v26, v27
	v_cvt_pk_bf16_f32 v19, v20, v21
	v_cvt_pk_bf16_f32 v7, v10, v11
	global_store_dwordx4 v[14:15], v[16:19], off
	global_store_dwordx4 v[14:15], v[4:7], off offset:32
	global_load_dwordx4 v[68:71], v[46:47], off offset:1040
	global_load_dwordx4 v[64:67], v[46:47], off offset:1024
	global_load_dwordx4 v[76:79], v[48:49], off offset:1040
	global_load_dwordx4 v[72:75], v[48:49], off offset:1024

; DEVI uint32_t pk(float a, float b) { const hwf32x2 v = {a, b}; return __builtin_bit_cast(uint32_t, __builtin_convertvector(v, hwbf16x2)); }
; __device__ void phase_gemm_qkv(const P& p, int vb, int nvb, char* smem) {
;     ...
;         const int r = tq + 16 * i; const float s = rs[r]; const int prow = mt * 128 + r;
;         if (d < 64) {
;           const float4 v0 = *(const float4*)(Ct + r * CT_LD + c8 * 8), v1 = *(const float4*)(Ct + r * CT_LD + c8 * 8 + 4);
;           *(uint4*)(Q + (size_t)prow * 768 + gc) = make_uint4(pk(v0.x * s, v0.y * s), pk(v0.z * s, v0.w * s), pk(v1.x * s, v1.y * s), pk(v1.z * s, v1.w * s));
;         } else if (d < 80) {
;           const int pos = prow % TP; float o1[8], o2[8];
; #pragma unroll
;           for (int e = 0; e < 8; e++) {
;             const int c = c8 * 8 + e; const int j = d - 64 + e;
;             const float x1 = Ct[r * CT_LD + c] * s, x2 = Ct[r * CT_LD + c + 16] * s;
;             const float cs = cost[pos * 16 + j], sn = sint[pos * 16 + j];
;             o1[e] = x1 * cs - x2 * sn; o2[e] = x2 * cs + x1 * sn;
;           }
;           *(uint4*)(Q + (size_t)prow * 768 + gc) = make_uint4(pk(o1[0], o1[1]), pk(o1[2], o1[3]), pk(o1[4], o1[5]), pk(o1[6], o1[7]));
;           *(uint4*)(Q + (size_t)prow * 768 + gc + 16) = make_uint4(pk(o2[0], o2[1]), pk(o2[2], o2[3]), pk(o2[4], o2[5]), pk(o2[6], o2[7]));
.LBB0_181:
	s_or_b64 exec, exec, s[0:1]
	s_waitcnt lgkmcnt(0)
	ds_read_b32 v10, v13 offset:64
	v_add_u32_e32 v4, 16, v12
	v_add_u32_e32 v14, s26, v4
	s_and_saveexec_b64 s[0:1], s[38:39]
	s_xor_b64 s[0:1], exec, s[0:1]
	s_cbranch_execz .LBB0_185
	s_and_saveexec_b64 s[66:67], vcc
	s_cbranch_execz .LBB0_184
	v_mul_hi_i32 v5, v14, s35
	v_lshrrev_b32_e32 v6, 31, v5
	v_ashrrev_i32_e32 v5, 10, v5
	v_add_u32_e32 v5, v5, v6
	v_mul_i32_i24_e32 v5, 0x1080, v5
	v_sub_u32_e32 v5, v14, v5
	v_mad_u64_u32 v[8:9], s[40:41], v4, s43, v[2:3]
	v_lshl_add_u32 v4, v5, 4, v3
	v_ashrrev_i32_e32 v5, 31, v4
	v_lshlrev_b64 v[4:5], 2, v[4:5]
	v_lshl_add_u64 v[20:21], s[68:69], 0, v[4:5]
	v_lshl_add_u64 v[36:37], s[28:29], 0, v[4:5]
	ds_read_b128 v[4:7], v8 offset:64
	s_nop 0
	ds_read_b128 v[24:27], v8
	ds_read_b128 v[28:31], v8 offset:16
	s_nop 0
	v_mad_i64_i32 v[14:15], s[40:41], v14, s36, v[0:1]
	s_waitcnt lgkmcnt(2)
	v_pk_mul_f32 v[4:5], v[10:11], v[4:5] op_sel_hi:[0,1]
	s_waitcnt lgkmcnt(1)
	v_pk_mul_f32 v[24:25], v[10:11], v[24:25] op_sel_hi:[0,1]
	v_pk_mul_f32 v[6:7], v[10:11], v[6:7] op_sel_hi:[0,1]
	s_waitcnt vmcnt(18)
	v_mov_b32_e32 v20, v80
	v_mov_b32_e32 v21, v81
	v_mov_b32_e32 v22, v82
	v_mov_b32_e32 v23, v83
	v_mov_b32_e32 v16, v84
	v_mov_b32_e32 v17, v85
	v_mov_b32_e32 v18, v86
	v_mov_b32_e32 v19, v87
	v_mov_b32_e32 v36, v88
	v_mov_b32_e32 v37, v89
	v_mov_b32_e32 v38, v90
	v_mov_b32_e32 v39, v91
	v_mov_b32_e32 v32, v92
	v_mov_b32_e32 v33, v93
	v_mov_b32_e32 v34, v94
	v_mov_b32_e32 v35, v95
	v_pk_mul_f32 v[40:41], v[4:5], v[36:37]
	s_nop 0
	v_pk_fma_f32 v[40:41], v[24:25], v[20:21], v[40:41] neg_lo:[0,0,1] neg_hi:[0,0,1]
	v_pk_mul_f32 v[24:25], v[24:25], v[36:37]
	s_nop 0
	v_pk_fma_f32 v[4:5], v[4:5], v[20:21], v[24:25]
	v_pk_mul_f32 v[20:21], v[10:11], v[26:27] op_sel_hi:[0,1]
	v_pk_mul_f32 v[24:25], v[6:7], v[38:39]
	v_cvt_pk_bf16_f32 v4, v4, v5
	v_pk_fma_f32 v[24:25], v[20:21], v[22:23], v[24:25] neg_lo:[0,0,1] neg_hi:[0,0,1]
	v_pk_mul_f32 v[20:21], v[20:21], v[38:39]
	s_nop 0
	v_pk_fma_f32 v[6:7], v[6:7], v[22:23], v[20:21]
	ds_read_b128 v[20:23], v8 offset:80
	v_cvt_pk_bf16_f32 v5, v6, v7
	s_waitcnt lgkmcnt(0)
	v_pk_mul_f32 v[8:9], v[10:11], v[20:21] op_sel_hi:[0,1]
	v_pk_mul_f32 v[20:21], v[10:11], v[28:29] op_sel_hi:[0,1]
	v_pk_mul_f32 v[26:27], v[8:9], v[32:33]
	s_nop 0
	v_pk_fma_f32 v[26:27], v[20:21], v[16:17], v[26:27] neg_lo:[0,0,1] neg_hi:[0,0,1]
	v_pk_mul_f32 v[20:21], v[20:21], v[32:33]
	s_nop 0
	v_pk_fma_f32 v[8:9], v[8:9], v[16:17], v[20:21]
	v_pk_mul_f32 v[16:17], v[10:11], v[22:23] op_sel_hi:[0,1]
	v_pk_mul_f32 v[10:11], v[10:11], v[30:31] op_sel_hi:[0,1]
	v_pk_mul_f32 v[20:21], v[16:17], v[34:35]
	v_cvt_pk_bf16_f32 v6, v8, v9
	v_pk_fma_f32 v[20:21], v[10:11], v[18:19], v[20:21] neg_lo:[0,0,1] neg_hi:[0,0,1]
	v_pk_mul_f32 v[10:11], v[10:11], v[34:35]
	s_nop 0
	v_pk_fma_f32 v[10:11], v[16:17], v[18:19], v[10:11]
	v_cvt_pk_bf16_f32 v16, v40, v41
	v_cvt_pk_bf16_f32 v17, v24, v25
	v_cvt_pk_bf16_f32 v18, v26, v27
	v_cvt_pk_bf16_f32 v19, v20, v21
	v_cvt_pk_bf16_f32 v7, v10, v11
	global_store_dwordx4 v[14:15], v[16:19], off
	global_store_dwordx4 v[14:15], v[4:7], off offset:32
	global_load_dwordx4 v[84:87], v[46:47], off offset:2064
	global_load_dwordx4 v[80:83], v[46:47], off offset:2048
	global_load_dwordx4 v[92:95], v[48:49], off offset:2064
	global_load_dwordx4 v[88:91], v[48:49], off offset:2048

; DEVI uint32_t pk(float a, float b) { const hwf32x2 v = {a, b}; return __builtin_bit_cast(uint32_t, __builtin_convertvector(v, hwbf16x2)); }
; __device__ void phase_gemm_qkv(const P& p, int vb, int nvb, char* smem) {
;     ...
;         const int r = tq + 16 * i; const float s = rs[r]; const int prow = mt * 128 + r;
;         if (d < 64) {
;           const float4 v0 = *(const float4*)(Ct + r * CT_LD + c8 * 8), v1 = *(const float4*)(Ct + r * CT_LD + c8 * 8 + 4);
;           *(uint4*)(Q + (size_t)prow * 768 + gc) = make_uint4(pk(v0.x * s, v0.y * s), pk(v0.z * s, v0.w * s), pk(v1.x * s, v1.y * s), pk(v1.z * s, v1.w * s));
;         } else if (d < 80) {
;           const int pos = prow % TP; float o1[8], o2[8];
; #pragma unroll
;           for (int e = 0; e < 8; e++) {
;             const int c = c8 * 8 + e; const int j = d - 64 + e;
;             const float x1 = Ct[r * CT_LD + c] * s, x2 = Ct[r * CT_LD + c + 16] * s;
;             const float cs = cost[pos * 16 + j], sn = sint[pos * 16 + j];
;             o1[e] = x1 * cs - x2 * sn; o2[e] = x2 * cs + x1 * sn;
;           }
;           *(uint4*)(Q + (size_t)prow * 768 + gc) = make_uint4(pk(o1[0], o1[1]), pk(o1[2], o1[3]), pk(o1[4], o1[5]), pk(o1[6], o1[7]));
;           *(uint4*)(Q + (size_t)prow * 768 + gc + 16) = make_uint4(pk(o2[0], o2[1]), pk(o2[2], o2[3]), pk(o2[4], o2[5]), pk(o2[6], o2[7]));
.LBB0_187:
	s_or_b64 exec, exec, s[0:1]
	s_waitcnt lgkmcnt(0)
	ds_read_b32 v10, v13 offset:128
	v_add_u32_e32 v4, 32, v12
	v_add_u32_e32 v14, s26, v4
	s_and_saveexec_b64 s[0:1], s[38:39]
	s_xor_b64 s[0:1], exec, s[0:1]
	s_cbranch_execz .LBB0_191
	s_and_saveexec_b64 s[66:67], vcc
	s_cbranch_execz .LBB0_190
	v_mul_hi_i32 v5, v14, s35
	v_lshrrev_b32_e32 v6, 31, v5
	v_ashrrev_i32_e32 v5, 10, v5
	v_add_u32_e32 v5, v5, v6
	v_mul_i32_i24_e32 v5, 0x1080, v5
	v_sub_u32_e32 v5, v14, v5
	v_mad_u64_u32 v[8:9], s[40:41], v4, s43, v[2:3]
	v_lshl_add_u32 v4, v5, 4, v3
	v_ashrrev_i32_e32 v5, 31, v4
	v_lshlrev_b64 v[4:5], 2, v[4:5]
	v_lshl_add_u64 v[20:21], s[68:69], 0, v[4:5]
	v_lshl_add_u64 v[36:37], s[28:29], 0, v[4:5]
	ds_read_b128 v[4:7], v8 offset:64
	s_nop 0
	ds_read_b128 v[24:27], v8
	ds_read_b128 v[28:31], v8 offset:16
	s_nop 0
	v_mad_i64_i32 v[14:15], s[40:41], v14, s36, v[0:1]
	s_waitcnt lgkmcnt(2)
	v_pk_mul_f32 v[4:5], v[10:11], v[4:5] op_sel_hi:[0,1]
	s_waitcnt lgkmcnt(1)
	v_pk_mul_f32 v[24:25], v[10:11], v[24:25] op_sel_hi:[0,1]
	v_pk_mul_f32 v[6:7], v[10:11], v[6:7] op_sel_hi:[0,1]
	s_waitcnt vmcnt(20)
	v_mov_b32_e32 v20, v96
	v_mov_b32_e32 v21, v97
	v_mov_b32_e32 v22, v98
	v_mov_b32_e32 v23, v99
	v_mov_b32_e32 v16, v100
	v_mov_b32_e32 v17, v101
	v_mov_b32_e32 v18, v102
	v_mov_b32_e32 v19, v103
	v_mov_b32_e32 v36, v104
	v_mov_b32_e32 v37, v105
	v_mov_b32_e32 v38, v106
	v_mov_b32_e32 v39, v107
	v_mov_b32_e32 v32, v108
	v_mov_b32_e32 v33, v109
	v_mov_b32_e32 v34, v110
	v_mov_b32_e32 v35, v111
	v_pk_mul_f32 v[40:41], v[4:5], v[36:37]
	s_nop 0
	v_pk_fma_f32 v[40:41], v[24:25], v[20:21], v[40:41] neg_lo:[0,0,1] neg_hi:[0,0,1]
	v_pk_mul_f32 v[24:25], v[24:25], v[36:37]
	s_nop 0
	v_pk_fma_f32 v[4:5], v[4:5], v[20:21], v[24:25]
	v_pk_mul_f32 v[20:21], v[10:11], v[26:27] op_sel_hi:[0,1]
	v_pk_mul_f32 v[24:25], v[6:7], v[38:39]
	v_cvt_pk_bf16_f32 v4, v4, v5
	v_pk_fma_f32 v[24:25], v[20:21], v[22:23], v[24:25] neg_lo:[0,0,1] neg_hi:[0,0,1]
	v_pk_mul_f32 v[20:21], v[20:21], v[38:39]
	s_nop 0
	v_pk_fma_f32 v[6:7], v[6:7], v[22:23], v[20:21]
	ds_read_b128 v[20:23], v8 offset:80
	v_cvt_pk_bf16_f32 v5, v6, v7
	s_waitcnt lgkmcnt(0)
	v_pk_mul_f32 v[8:9], v[10:11], v[20:21] op_sel_hi:[0,1]
	v_pk_mul_f32 v[20:21], v[10:11], v[28:29] op_sel_hi:[0,1]
	v_pk_mul_f32 v[26:27], v[8:9], v[32:33]
	s_nop 0
	v_pk_fma_f32 v[26:27], v[20:21], v[16:17], v[26:27] neg_lo:[0,0,1] neg_hi:[0,0,1]
	v_pk_mul_f32 v[20:21], v[20:21], v[32:33]
	s_nop 0
	v_pk_fma_f32 v[8:9], v[8:9], v[16:17], v[20:21]
	v_pk_mul_f32 v[16:17], v[10:11], v[22:23] op_sel_hi:[0,1]
	v_pk_mul_f32 v[10:11], v[10:11], v[30:31] op_sel_hi:[0,1]
	v_pk_mul_f32 v[20:21], v[16:17], v[34:35]
	v_cvt_pk_bf16_f32 v6, v8, v9
	v_pk_fma_f32 v[20:21], v[10:11], v[18:19], v[20:21] neg_lo:[0,0,1] neg_hi:[0,0,1]
	v_pk_mul_f32 v[10:11], v[10:11], v[34:35]
	s_nop 0
	v_pk_fma_f32 v[10:11], v[16:17], v[18:19], v[10:11]
	v_cvt_pk_bf16_f32 v16, v40, v41
	v_cvt_pk_bf16_f32 v17, v24, v25
	v_cvt_pk_bf16_f32 v18, v26, v27
	v_cvt_pk_bf16_f32 v19, v20, v21
	v_cvt_pk_bf16_f32 v7, v10, v11
	global_store_dwordx4 v[14:15], v[16:19], off
	global_store_dwordx4 v[14:15], v[4:7], off offset:32
	global_load_dwordx4 v[100:103], v[46:47], off offset:3088
	global_load_dwordx4 v[96:99], v[46:47], off offset:3072
	global_load_dwordx4 v[108:111], v[48:49], off offset:3088
	global_load_dwordx4 v[104:107], v[48:49], off offset:3072

; DEVI uint32_t pk(float a, float b) { const hwf32x2 v = {a, b}; return __builtin_bit_cast(uint32_t, __builtin_convertvector(v, hwbf16x2)); }
; __device__ void phase_gemm_qkv(const P& p, int vb, int nvb, char* smem) {
;     ...
;         const int r = tq + 16 * i; const float s = rs[r]; const int prow = mt * 128 + r;
;         if (d < 64) {
;           const float4 v0 = *(const float4*)(Ct + r * CT_LD + c8 * 8), v1 = *(const float4*)(Ct + r * CT_LD + c8 * 8 + 4);
;           *(uint4*)(Q + (size_t)prow * 768 + gc) = make_uint4(pk(v0.x * s, v0.y * s), pk(v0.z * s, v0.w * s), pk(v1.x * s, v1.y * s), pk(v1.z * s, v1.w * s));
;         } else if (d < 80) {
;           const int pos = prow % TP; float o1[8], o2[8];
; #pragma unroll
;           for (int e = 0; e < 8; e++) {
;             const int c = c8 * 8 + e; const int j = d - 64 + e;
;             const float x1 = Ct[r * CT_LD + c] * s, x2 = Ct[r * CT_LD + c + 16] * s;
;             const float cs = cost[pos * 16 + j], sn = sint[pos * 16 + j];
;             o1[e] = x1 * cs - x2 * sn; o2[e] = x2 * cs + x1 * sn;
;           }
;           *(uint4*)(Q + (size_t)prow * 768 + gc) = make_uint4(pk(o1[0], o1[1]), pk(o1[2], o1[3]), pk(o1[4], o1[5]), pk(o1[6], o1[7]));
;           *(uint4*)(Q + (size_t)prow * 768 + gc + 16) = make_uint4(pk(o2[0], o2[1]), pk(o2[2], o2[3]), pk(o2[4], o2[5]), pk(o2[6], o2[7]));
.LBB0_193:
	s_or_b64 exec, exec, s[0:1]
	s_waitcnt lgkmcnt(0)
	ds_read_b32 v10, v13 offset:192
	v_add_u32_e32 v4, 48, v12
	v_add_u32_e32 v14, s26, v4
	s_and_saveexec_b64 s[0:1], s[38:39]
	s_xor_b64 s[0:1], exec, s[0:1]
	s_cbranch_execz .LBB0_197
	s_and_saveexec_b64 s[66:67], vcc
	s_cbranch_execz .LBB0_196
	v_mul_hi_i32 v5, v14, s35
	v_lshrrev_b32_e32 v6, 31, v5
	v_ashrrev_i32_e32 v5, 10, v5
	v_add_u32_e32 v5, v5, v6
	v_mul_i32_i24_e32 v5, 0x1080, v5
	v_sub_u32_e32 v5, v14, v5
	v_mad_u64_u32 v[8:9], s[40:41], v4, s43, v[2:3]
	v_lshl_add_u32 v4, v5, 4, v3
	v_ashrrev_i32_e32 v5, 31, v4
	v_lshlrev_b64 v[4:5], 2, v[4:5]
	v_lshl_add_u64 v[20:21], s[68:69], 0, v[4:5]
	v_lshl_add_u64 v[36:37], s[28:29], 0, v[4:5]
	ds_read_b128 v[4:7], v8 offset:64
	s_nop 0
	ds_read_b128 v[24:27], v8
	ds_read_b128 v[28:31], v8 offset:16
	s_nop 0
	v_mad_i64_i32 v[14:15], s[40:41], v14, s36, v[0:1]
	s_waitcnt lgkmcnt(2)
	v_pk_mul_f32 v[4:5], v[10:11], v[4:5] op_sel_hi:[0,1]
	s_waitcnt lgkmcnt(1)
	v_pk_mul_f32 v[24:25], v[10:11], v[24:25] op_sel_hi:[0,1]
	v_pk_mul_f32 v[6:7], v[10:11], v[6:7] op_sel_hi:[0,1]
	s_waitcnt vmcnt(22)
	v_mov_b32_e32 v20, v112
	v_mov_b32_e32 v21, v113
	v_mov_b32_e32 v22, v114
	v_mov_b32_e32 v23, v115
	v_mov_b32_e32 v16, v116
	v_mov_b32_e32 v17, v117
	v_mov_b32_e32 v18, v118
	v_mov_b32_e32 v19, v119
	v_mov_b32_e32 v36, v120
	v_mov_b32_e32 v37, v121
	v_mov_b32_e32 v38, v122
	v_mov_b32_e32 v39, v123
	v_mov_b32_e32 v32, v124
	v_mov_b32_e32 v33, v125
	v_mov_b32_e32 v34, v126
	v_mov_b32_e32 v35, v127
	v_pk_mul_f32 v[40:41], v[4:5], v[36:37]
	s_nop 0
	v_pk_fma_f32 v[40:41], v[24:25], v[20:21], v[40:41] neg_lo:[0,0,1] neg_hi:[0,0,1]
	v_pk_mul_f32 v[24:25], v[24:25], v[36:37]
	s_nop 0
	v_pk_fma_f32 v[4:5], v[4:5], v[20:21], v[24:25]
	v_pk_mul_f32 v[20:21], v[10:11], v[26:27] op_sel_hi:[0,1]
	v_pk_mul_f32 v[24:25], v[6:7], v[38:39]
	v_cvt_pk_bf16_f32 v4, v4, v5
	v_pk_fma_f32 v[24:25], v[20:21], v[22:23], v[24:25] neg_lo:[0,0,1] neg_hi:[0,0,1]
	v_pk_mul_f32 v[20:21], v[20:21], v[38:39]
	s_nop 0
	v_pk_fma_f32 v[6:7], v[6:7], v[22:23], v[20:21]
	ds_read_b128 v[20:23], v8 offset:80
	v_cvt_pk_bf16_f32 v5, v6, v7
	s_waitcnt lgkmcnt(0)
	v_pk_mul_f32 v[8:9], v[10:11], v[20:21] op_sel_hi:[0,1]
	v_pk_mul_f32 v[20:21], v[10:11], v[28:29] op_sel_hi:[0,1]
	v_pk_mul_f32 v[26:27], v[8:9], v[32:33]
	s_nop 0
	v_pk_fma_f32 v[26:27], v[20:21], v[16:17], v[26:27] neg_lo:[0,0,1] neg_hi:[0,0,1]
	v_pk_mul_f32 v[20:21], v[20:21], v[32:33]
	s_nop 0
	v_pk_fma_f32 v[8:9], v[8:9], v[16:17], v[20:21]
	v_pk_mul_f32 v[16:17], v[10:11], v[22:23] op_sel_hi:[0,1]
	v_pk_mul_f32 v[10:11], v[10:11], v[30:31] op_sel_hi:[0,1]
	v_pk_mul_f32 v[20:21], v[16:17], v[34:35]
	v_cvt_pk_bf16_f32 v6, v8, v9
	v_pk_fma_f32 v[20:21], v[10:11], v[18:19], v[20:21] neg_lo:[0,0,1] neg_hi:[0,0,1]
	v_pk_mul_f32 v[10:11], v[10:11], v[34:35]
	s_nop 0
	v_pk_fma_f32 v[10:11], v[16:17], v[18:19], v[10:11]
	v_cvt_pk_bf16_f32 v16, v40, v41
	v_cvt_pk_bf16_f32 v17, v24, v25
	v_cvt_pk_bf16_f32 v18, v26, v27
	v_cvt_pk_bf16_f32 v19, v20, v21
	v_cvt_pk_bf16_f32 v7, v10, v11
	global_store_dwordx4 v[14:15], v[16:19], off
	global_store_dwordx4 v[14:15], v[4:7], off offset:32

; DEVI uint32_t pk(float a, float b) { const hwf32x2 v = {a, b}; return __builtin_bit_cast(uint32_t, __builtin_convertvector(v, hwbf16x2)); }
; __device__ void phase_gemm_qkv(const P& p, int vb, int nvb, char* smem) {
;     ...
;         const int r = tq + 16 * i; const float s = rs[r]; const int prow = mt * 128 + r;
;         if (d < 64) {
;           const float4 v0 = *(const float4*)(Ct + r * CT_LD + c8 * 8), v1 = *(const float4*)(Ct + r * CT_LD + c8 * 8 + 4);
;           *(uint4*)(Q + (size_t)prow * 768 + gc) = make_uint4(pk(v0.x * s, v0.y * s), pk(v0.z * s, v0.w * s), pk(v1.x * s, v1.y * s), pk(v1.z * s, v1.w * s));
;         } else if (d < 80) {
;           const int pos = prow % TP; float o1[8], o2[8];
; #pragma unroll
;           for (int e = 0; e < 8; e++) {
;             const int c = c8 * 8 + e; const int j = d - 64 + e;
;             const float x1 = Ct[r * CT_LD + c] * s, x2 = Ct[r * CT_LD + c + 16] * s;
;             const float cs = cost[pos * 16 + j], sn = sint[pos * 16 + j];
;             o1[e] = x1 * cs - x2 * sn; o2[e] = x2 * cs + x1 * sn;
;           }
;           *(uint4*)(Q + (size_t)prow * 768 + gc) = make_uint4(pk(o1[0], o1[1]), pk(o1[2], o1[3]), pk(o1[4], o1[5]), pk(o1[6], o1[7]));
;           *(uint4*)(Q + (size_t)prow * 768 + gc + 16) = make_uint4(pk(o2[0], o2[1]), pk(o2[2], o2[3]), pk(o2[4], o2[5]), pk(o2[6], o2[7]));
.LBB0_199:
	s_or_b64 exec, exec, s[0:1]
	s_waitcnt lgkmcnt(0)
	ds_read_b32 v10, v13 offset:256
	v_add_u32_e32 v4, 64, v12
	v_add_u32_e32 v14, s26, v4
	s_and_saveexec_b64 s[0:1], s[38:39]
	s_xor_b64 s[0:1], exec, s[0:1]
	s_cbranch_execz .LBB0_203
	s_and_saveexec_b64 s[66:67], vcc
	s_cbranch_execz .LBB0_202
	v_mul_hi_i32 v5, v14, s35
	v_lshrrev_b32_e32 v6, 31, v5
	v_ashrrev_i32_e32 v5, 10, v5
	v_add_u32_e32 v5, v5, v6
	v_mul_i32_i24_e32 v5, 0x1080, v5
	v_sub_u32_e32 v5, v14, v5
	v_mad_u64_u32 v[8:9], s[40:41], v4, s43, v[2:3]
	v_lshl_add_u32 v4, v5, 4, v3
	v_ashrrev_i32_e32 v5, 31, v4
	v_lshlrev_b64 v[4:5], 2, v[4:5]
	v_lshl_add_u64 v[20:21], s[68:69], 0, v[4:5]
	v_lshl_add_u64 v[36:37], s[28:29], 0, v[4:5]
	ds_read_b128 v[4:7], v8 offset:64
	s_nop 0
	ds_read_b128 v[24:27], v8
	ds_read_b128 v[28:31], v8 offset:16
	s_nop 0
	v_mad_i64_i32 v[14:15], s[40:41], v14, s36, v[0:1]
	s_waitcnt lgkmcnt(2)
	v_pk_mul_f32 v[4:5], v[10:11], v[4:5] op_sel_hi:[0,1]
	s_waitcnt lgkmcnt(1)
	v_pk_mul_f32 v[24:25], v[10:11], v[24:25] op_sel_hi:[0,1]
	v_pk_mul_f32 v[6:7], v[10:11], v[6:7] op_sel_hi:[0,1]
	s_waitcnt vmcnt(20)
	v_mov_b32_e32 v20, v128
	v_mov_b32_e32 v21, v129
	v_mov_b32_e32 v22, v130
	v_mov_b32_e32 v23, v131
	v_mov_b32_e32 v16, v132
	v_mov_b32_e32 v17, v133
	v_mov_b32_e32 v18, v134
	v_mov_b32_e32 v19, v135
	v_mov_b32_e32 v36, v136
	v_mov_b32_e32 v37, v137
	v_mov_b32_e32 v38, v138
	v_mov_b32_e32 v39, v139
	v_mov_b32_e32 v32, v140
	v_mov_b32_e32 v33, v141
	v_mov_b32_e32 v34, v142
	v_mov_b32_e32 v35, v143
	v_pk_mul_f32 v[40:41], v[4:5], v[36:37]
	s_nop 0
	v_pk_fma_f32 v[40:41], v[24:25], v[20:21], v[40:41] neg_lo:[0,0,1] neg_hi:[0,0,1]
	v_pk_mul_f32 v[24:25], v[24:25], v[36:37]
	s_nop 0
	v_pk_fma_f32 v[4:5], v[4:5], v[20:21], v[24:25]
	v_pk_mul_f32 v[20:21], v[10:11], v[26:27] op_sel_hi:[0,1]
	v_pk_mul_f32 v[24:25], v[6:7], v[38:39]
	v_cvt_pk_bf16_f32 v4, v4, v5
	v_pk_fma_f32 v[24:25], v[20:21], v[22:23], v[24:25] neg_lo:[0,0,1] neg_hi:[0,0,1]
	v_pk_mul_f32 v[20:21], v[20:21], v[38:39]
	s_nop 0
	v_pk_fma_f32 v[6:7], v[6:7], v[22:23], v[20:21]
	ds_read_b128 v[20:23], v8 offset:80
	v_cvt_pk_bf16_f32 v5, v6, v7
	s_waitcnt lgkmcnt(0)
	v_pk_mul_f32 v[8:9], v[10:11], v[20:21] op_sel_hi:[0,1]
	v_pk_mul_f32 v[20:21], v[10:11], v[28:29] op_sel_hi:[0,1]
	v_pk_mul_f32 v[26:27], v[8:9], v[32:33]
	s_nop 0
	v_pk_fma_f32 v[26:27], v[20:21], v[16:17], v[26:27] neg_lo:[0,0,1] neg_hi:[0,0,1]
	v_pk_mul_f32 v[20:21], v[20:21], v[32:33]
	s_nop 0
	v_pk_fma_f32 v[8:9], v[8:9], v[16:17], v[20:21]
	v_pk_mul_f32 v[16:17], v[10:11], v[22:23] op_sel_hi:[0,1]
	v_pk_mul_f32 v[10:11], v[10:11], v[30:31] op_sel_hi:[0,1]
	v_pk_mul_f32 v[20:21], v[16:17], v[34:35]
	v_cvt_pk_bf16_f32 v6, v8, v9
	v_pk_fma_f32 v[20:21], v[10:11], v[18:19], v[20:21] neg_lo:[0,0,1] neg_hi:[0,0,1]
	v_pk_mul_f32 v[10:11], v[10:11], v[34:35]
	s_nop 0
	v_pk_fma_f32 v[10:11], v[16:17], v[18:19], v[10:11]
	v_cvt_pk_bf16_f32 v16, v40, v41
	v_cvt_pk_bf16_f32 v17, v24, v25
	v_cvt_pk_bf16_f32 v18, v26, v27
	v_cvt_pk_bf16_f32 v19, v20, v21
	v_cvt_pk_bf16_f32 v7, v10, v11
	global_store_dwordx4 v[14:15], v[16:19], off
	global_store_dwordx4 v[14:15], v[4:7], off offset:32

; DEVI uint32_t pk(float a, float b) { const hwf32x2 v = {a, b}; return __builtin_bit_cast(uint32_t, __builtin_convertvector(v, hwbf16x2)); }
; __device__ void phase_gemm_qkv(const P& p, int vb, int nvb, char* smem) {
;     ...
;         const int r = tq + 16 * i; const float s = rs[r]; const int prow = mt * 128 + r;
;         if (d < 64) {
;           const float4 v0 = *(const float4*)(Ct + r * CT_LD + c8 * 8), v1 = *(const float4*)(Ct + r * CT_LD + c8 * 8 + 4);
;           *(uint4*)(Q + (size_t)prow * 768 + gc) = make_uint4(pk(v0.x * s, v0.y * s), pk(v0.z * s, v0.w * s), pk(v1.x * s, v1.y * s), pk(v1.z * s, v1.w * s));
;         } else if (d < 80) {
;           const int pos = prow % TP; float o1[8], o2[8];
; #pragma unroll
;           for (int e = 0; e < 8; e++) {
;             const int c = c8 * 8 + e; const int j = d - 64 + e;
;             const float x1 = Ct[r * CT_LD + c] * s, x2 = Ct[r * CT_LD + c + 16] * s;
;             const float cs = cost[pos * 16 + j], sn = sint[pos * 16 + j];
;             o1[e] = x1 * cs - x2 * sn; o2[e] = x2 * cs + x1 * sn;
;           }
;           *(uint4*)(Q + (size_t)prow * 768 + gc) = make_uint4(pk(o1[0], o1[1]), pk(o1[2], o1[3]), pk(o1[4], o1[5]), pk(o1[6], o1[7]));
;           *(uint4*)(Q + (size_t)prow * 768 + gc + 16) = make_uint4(pk(o2[0], o2[1]), pk(o2[2], o2[3]), pk(o2[4], o2[5]), pk(o2[6], o2[7]));
.LBB0_205:
	s_or_b64 exec, exec, s[0:1]
	s_waitcnt lgkmcnt(0)
	ds_read_b32 v10, v13 offset:320
	v_add_u32_e32 v4, 0x50, v12
	v_add_u32_e32 v14, s26, v4
	s_and_saveexec_b64 s[0:1], s[38:39]
	s_xor_b64 s[0:1], exec, s[0:1]
	s_cbranch_execz .LBB0_209
	s_and_saveexec_b64 s[66:67], vcc
	s_cbranch_execz .LBB0_208
	v_mul_hi_i32 v5, v14, s35
	v_lshrrev_b32_e32 v6, 31, v5
	v_ashrrev_i32_e32 v5, 10, v5
	v_add_u32_e32 v5, v5, v6
	v_mul_i32_i24_e32 v5, 0x1080, v5
	v_sub_u32_e32 v5, v14, v5
	v_mad_u64_u32 v[8:9], s[40:41], v4, s43, v[2:3]
	v_lshl_add_u32 v4, v5, 4, v3
	v_ashrrev_i32_e32 v5, 31, v4
	v_lshlrev_b64 v[4:5], 2, v[4:5]
	v_lshl_add_u64 v[20:21], s[68:69], 0, v[4:5]
	v_lshl_add_u64 v[36:37], s[28:29], 0, v[4:5]
	ds_read_b128 v[4:7], v8 offset:64
	s_nop 0
	ds_read_b128 v[24:27], v8
	ds_read_b128 v[28:31], v8 offset:16
	s_nop 0
	v_mad_i64_i32 v[14:15], s[40:41], v14, s36, v[0:1]
	s_waitcnt lgkmcnt(2)
	v_pk_mul_f32 v[4:5], v[10:11], v[4:5] op_sel_hi:[0,1]
	s_waitcnt lgkmcnt(1)
	v_pk_mul_f32 v[24:25], v[10:11], v[24:25] op_sel_hi:[0,1]
	v_pk_mul_f32 v[6:7], v[10:11], v[6:7] op_sel_hi:[0,1]
	s_waitcnt vmcnt(16)
	v_mov_b32_e32 v20, v64
	v_mov_b32_e32 v21, v65
	v_mov_b32_e32 v22, v66
	v_mov_b32_e32 v23, v67
	v_mov_b32_e32 v16, v68
	v_mov_b32_e32 v17, v69
	v_mov_b32_e32 v18, v70
	v_mov_b32_e32 v19, v71
	v_mov_b32_e32 v36, v72
	v_mov_b32_e32 v37, v73
	v_mov_b32_e32 v38, v74
	v_mov_b32_e32 v39, v75
	v_mov_b32_e32 v32, v76
	v_mov_b32_e32 v33, v77
	v_mov_b32_e32 v34, v78
	v_mov_b32_e32 v35, v79
	v_pk_mul_f32 v[40:41], v[4:5], v[36:37]
	s_nop 0
	v_pk_fma_f32 v[40:41], v[24:25], v[20:21], v[40:41] neg_lo:[0,0,1] neg_hi:[0,0,1]
	v_pk_mul_f32 v[24:25], v[24:25], v[36:37]
	s_nop 0
	v_pk_fma_f32 v[4:5], v[4:5], v[20:21], v[24:25]
	v_pk_mul_f32 v[20:21], v[10:11], v[26:27] op_sel_hi:[0,1]
	v_pk_mul_f32 v[24:25], v[6:7], v[38:39]
	v_cvt_pk_bf16_f32 v4, v4, v5
	v_pk_fma_f32 v[24:25], v[20:21], v[22:23], v[24:25] neg_lo:[0,0,1] neg_hi:[0,0,1]
	v_pk_mul_f32 v[20:21], v[20:21], v[38:39]
	s_nop 0
	v_pk_fma_f32 v[6:7], v[6:7], v[22:23], v[20:21]
	ds_read_b128 v[20:23], v8 offset:80
	v_cvt_pk_bf16_f32 v5, v6, v7
	s_waitcnt lgkmcnt(0)
	v_pk_mul_f32 v[8:9], v[10:11], v[20:21] op_sel_hi:[0,1]
	v_pk_mul_f32 v[20:21], v[10:11], v[28:29] op_sel_hi:[0,1]
	v_pk_mul_f32 v[26:27], v[8:9], v[32:33]
	s_nop 0
	v_pk_fma_f32 v[26:27], v[20:21], v[16:17], v[26:27] neg_lo:[0,0,1] neg_hi:[0,0,1]
	v_pk_mul_f32 v[20:21], v[20:21], v[32:33]
	s_nop 0
	v_pk_fma_f32 v[8:9], v[8:9], v[16:17], v[20:21]
	v_pk_mul_f32 v[16:17], v[10:11], v[22:23] op_sel_hi:[0,1]
	v_pk_mul_f32 v[10:11], v[10:11], v[30:31] op_sel_hi:[0,1]
	v_pk_mul_f32 v[20:21], v[16:17], v[34:35]
	v_cvt_pk_bf16_f32 v6, v8, v9
	v_pk_fma_f32 v[20:21], v[10:11], v[18:19], v[20:21] neg_lo:[0,0,1] neg_hi:[0,0,1]
	v_pk_mul_f32 v[10:11], v[10:11], v[34:35]
	s_nop 0
	v_pk_fma_f32 v[10:11], v[16:17], v[18:19], v[10:11]
	v_cvt_pk_bf16_f32 v16, v40, v41
	v_cvt_pk_bf16_f32 v17, v24, v25
	v_cvt_pk_bf16_f32 v18, v26, v27
	v_cvt_pk_bf16_f32 v19, v20, v21
	v_cvt_pk_bf16_f32 v7, v10, v11
	global_store_dwordx4 v[14:15], v[16:19], off
	global_store_dwordx4 v[14:15], v[4:7], off offset:32

; DEVI uint32_t pk(float a, float b) { const hwf32x2 v = {a, b}; return __builtin_bit_cast(uint32_t, __builtin_convertvector(v, hwbf16x2)); }
; __device__ void phase_gemm_qkv(const P& p, int vb, int nvb, char* smem) {
;     ...
;         const int r = tq + 16 * i; const float s = rs[r]; const int prow = mt * 128 + r;
;         if (d < 64) {
;           const float4 v0 = *(const float4*)(Ct + r * CT_LD + c8 * 8), v1 = *(const float4*)(Ct + r * CT_LD + c8 * 8 + 4);
;           *(uint4*)(Q + (size_t)prow * 768 + gc) = make_uint4(pk(v0.x * s, v0.y * s), pk(v0.z * s, v0.w * s), pk(v1.x * s, v1.y * s), pk(v1.z * s, v1.w * s));
;         } else if (d < 80) {
;           const int pos = prow % TP; float o1[8], o2[8];
; #pragma unroll
;           for (int e = 0; e < 8; e++) {
;             const int c = c8 * 8 + e; const int j = d - 64 + e;
;             const float x1 = Ct[r * CT_LD + c] * s, x2 = Ct[r * CT_LD + c + 16] * s;
;             const float cs = cost[pos * 16 + j], sn = sint[pos * 16 + j];
;             o1[e] = x1 * cs - x2 * sn; o2[e] = x2 * cs + x1 * sn;
;           }
;           *(uint4*)(Q + (size_t)prow * 768 + gc) = make_uint4(pk(o1[0], o1[1]), pk(o1[2], o1[3]), pk(o1[4], o1[5]), pk(o1[6], o1[7]));
;           *(uint4*)(Q + (size_t)prow * 768 + gc + 16) = make_uint4(pk(o2[0], o2[1]), pk(o2[2], o2[3]), pk(o2[4], o2[5]), pk(o2[6], o2[7]));
.LBB0_211:
	s_or_b64 exec, exec, s[0:1]
	s_waitcnt lgkmcnt(0)
	ds_read_b32 v10, v13 offset:384
	v_add_u32_e32 v4, 0x60, v12
	v_add_u32_e32 v14, s26, v4
	s_and_saveexec_b64 s[0:1], s[38:39]
	s_xor_b64 s[0:1], exec, s[0:1]
	s_cbranch_execz .LBB0_215
	s_and_saveexec_b64 s[66:67], vcc
	s_cbranch_execz .LBB0_214
	v_mul_hi_i32 v5, v14, s35
	v_lshrrev_b32_e32 v6, 31, v5
	v_ashrrev_i32_e32 v5, 10, v5
	v_add_u32_e32 v5, v5, v6
	v_mul_i32_i24_e32 v5, 0x1080, v5
	v_sub_u32_e32 v5, v14, v5
	v_mad_u64_u32 v[8:9], s[40:41], v4, s43, v[2:3]
	v_lshl_add_u32 v4, v5, 4, v3
	v_ashrrev_i32_e32 v5, 31, v4
	v_lshlrev_b64 v[4:5], 2, v[4:5]
	v_lshl_add_u64 v[20:21], s[68:69], 0, v[4:5]
	v_lshl_add_u64 v[36:37], s[28:29], 0, v[4:5]
	ds_read_b128 v[4:7], v8 offset:64
	s_nop 0
	ds_read_b128 v[24:27], v8
	ds_read_b128 v[28:31], v8 offset:16
	s_nop 0
	v_mad_i64_i32 v[14:15], s[40:41], v14, s36, v[0:1]
	s_waitcnt lgkmcnt(2)
	v_pk_mul_f32 v[4:5], v[10:11], v[4:5] op_sel_hi:[0,1]
	s_waitcnt lgkmcnt(1)
	v_pk_mul_f32 v[24:25], v[10:11], v[24:25] op_sel_hi:[0,1]
	v_pk_mul_f32 v[6:7], v[10:11], v[6:7] op_sel_hi:[0,1]
	s_waitcnt vmcnt(12)
	v_mov_b32_e32 v20, v80
	v_mov_b32_e32 v21, v81
	v_mov_b32_e32 v22, v82
	v_mov_b32_e32 v23, v83
	v_mov_b32_e32 v16, v84
	v_mov_b32_e32 v17, v85
	v_mov_b32_e32 v18, v86
	v_mov_b32_e32 v19, v87
	v_mov_b32_e32 v36, v88
	v_mov_b32_e32 v37, v89
	v_mov_b32_e32 v38, v90
	v_mov_b32_e32 v39, v91
	v_mov_b32_e32 v32, v92
	v_mov_b32_e32 v33, v93
	v_mov_b32_e32 v34, v94
	v_mov_b32_e32 v35, v95
	v_pk_mul_f32 v[40:41], v[4:5], v[36:37]
	s_nop 0
	v_pk_fma_f32 v[40:41], v[24:25], v[20:21], v[40:41] neg_lo:[0,0,1] neg_hi:[0,0,1]
	v_pk_mul_f32 v[24:25], v[24:25], v[36:37]
	s_nop 0
	v_pk_fma_f32 v[4:5], v[4:5], v[20:21], v[24:25]
	v_pk_mul_f32 v[20:21], v[10:11], v[26:27] op_sel_hi:[0,1]
	v_pk_mul_f32 v[24:25], v[6:7], v[38:39]
	v_cvt_pk_bf16_f32 v4, v4, v5
	v_pk_fma_f32 v[24:25], v[20:21], v[22:23], v[24:25] neg_lo:[0,0,1] neg_hi:[0,0,1]
	v_pk_mul_f32 v[20:21], v[20:21], v[38:39]
	s_nop 0
	v_pk_fma_f32 v[6:7], v[6:7], v[22:23], v[20:21]
	ds_read_b128 v[20:23], v8 offset:80
	v_cvt_pk_bf16_f32 v5, v6, v7
	s_waitcnt lgkmcnt(0)
	v_pk_mul_f32 v[8:9], v[10:11], v[20:21] op_sel_hi:[0,1]
	v_pk_mul_f32 v[20:21], v[10:11], v[28:29] op_sel_hi:[0,1]
	v_pk_mul_f32 v[26:27], v[8:9], v[32:33]
	s_nop 0
	v_pk_fma_f32 v[26:27], v[20:21], v[16:17], v[26:27] neg_lo:[0,0,1] neg_hi:[0,0,1]
	v_pk_mul_f32 v[20:21], v[20:21], v[32:33]
	s_nop 0
	v_pk_fma_f32 v[8:9], v[8:9], v[16:17], v[20:21]
	v_pk_mul_f32 v[16:17], v[10:11], v[22:23] op_sel_hi:[0,1]
	v_pk_mul_f32 v[10:11], v[10:11], v[30:31] op_sel_hi:[0,1]
	v_pk_mul_f32 v[20:21], v[16:17], v[34:35]
	v_cvt_pk_bf16_f32 v6, v8, v9
	v_pk_fma_f32 v[20:21], v[10:11], v[18:19], v[20:21] neg_lo:[0,0,1] neg_hi:[0,0,1]
	v_pk_mul_f32 v[10:11], v[10:11], v[34:35]
	s_nop 0
	v_pk_fma_f32 v[10:11], v[16:17], v[18:19], v[10:11]
	v_cvt_pk_bf16_f32 v16, v40, v41
	v_cvt_pk_bf16_f32 v17, v24, v25
	v_cvt_pk_bf16_f32 v18, v26, v27
	v_cvt_pk_bf16_f32 v19, v20, v21
	v_cvt_pk_bf16_f32 v7, v10, v11
	global_store_dwordx4 v[14:15], v[16:19], off
	global_store_dwordx4 v[14:15], v[4:7], off offset:32

; DEVI uint32_t pk(float a, float b) { const hwf32x2 v = {a, b}; return __builtin_bit_cast(uint32_t, __builtin_convertvector(v, hwbf16x2)); }
; __device__ void phase_gemm_qkv(const P& p, int vb, int nvb, char* smem) {
;     ...
;         const int r = tq + 16 * i; const float s = rs[r]; const int prow = mt * 128 + r;
;         if (d < 64) {
;           const float4 v0 = *(const float4*)(Ct + r * CT_LD + c8 * 8), v1 = *(const float4*)(Ct + r * CT_LD + c8 * 8 + 4);
;           *(uint4*)(Q + (size_t)prow * 768 + gc) = make_uint4(pk(v0.x * s, v0.y * s), pk(v0.z * s, v0.w * s), pk(v1.x * s, v1.y * s), pk(v1.z * s, v1.w * s));
;         } else if (d < 80) {
;           const int pos = prow % TP; float o1[8], o2[8];
; #pragma unroll
;           for (int e = 0; e < 8; e++) {
;             const int c = c8 * 8 + e; const int j = d - 64 + e;
;             const float x1 = Ct[r * CT_LD + c] * s, x2 = Ct[r * CT_LD + c + 16] * s;
;             const float cs = cost[pos * 16 + j], sn = sint[pos * 16 + j];
;             o1[e] = x1 * cs - x2 * sn; o2[e] = x2 * cs + x1 * sn;
;           }
;           *(uint4*)(Q + (size_t)prow * 768 + gc) = make_uint4(pk(o1[0], o1[1]), pk(o1[2], o1[3]), pk(o1[4], o1[5]), pk(o1[6], o1[7]));
;           *(uint4*)(Q + (size_t)prow * 768 + gc + 16) = make_uint4(pk(o2[0], o2[1]), pk(o2[2], o2[3]), pk(o2[4], o2[5]), pk(o2[6], o2[7]));
.LBB0_217:
	s_or_b64 exec, exec, s[0:1]
	ds_read_b32 v8, v13 offset:448
	v_add_u32_e32 v4, 0x70, v12
	s_waitcnt lgkmcnt(1)
	v_add_u32_e32 v10, s26, v4
	s_and_saveexec_b64 s[0:1], s[38:39]
	s_xor_b64 s[0:1], exec, s[0:1]
	s_cbranch_execz .LBB0_221
	s_and_saveexec_b64 s[38:39], vcc
	s_cbranch_execz .LBB0_220
	v_mul_hi_i32 v5, v10, s35
	v_lshrrev_b32_e32 v6, 31, v5
	v_ashrrev_i32_e32 v5, 10, v5
	v_add_u32_e32 v5, v5, v6
	v_mul_i32_i24_e32 v5, 0x1080, v5
	v_sub_u32_e32 v5, v10, v5
	v_mad_u64_u32 v[6:7], s[40:41], v4, s43, v[2:3]
	v_lshl_add_u32 v2, v5, 4, v3
	v_ashrrev_i32_e32 v3, 31, v2
	v_lshlrev_b64 v[2:3], 2, v[2:3]
	v_lshl_add_u64 v[16:17], s[68:69], 0, v[2:3]
	v_lshl_add_u64 v[32:33], s[28:29], 0, v[2:3]
	ds_read_b128 v[2:5], v6 offset:64
	s_nop 0
	ds_read_b128 v[20:23], v6
	ds_read_b128 v[24:27], v6 offset:16
	s_nop 0
	v_mad_i64_i32 v[10:11], s[40:41], v10, s36, v[0:1]
	s_waitcnt lgkmcnt(2)
	v_pk_mul_f32 v[2:3], v[8:9], v[2:3] op_sel_hi:[0,1]
	s_waitcnt lgkmcnt(1)
	v_pk_mul_f32 v[20:21], v[8:9], v[20:21] op_sel_hi:[0,1]
	v_pk_mul_f32 v[4:5], v[8:9], v[4:5] op_sel_hi:[0,1]
	s_waitcnt vmcnt(8)
	v_mov_b32_e32 v16, v96
	v_mov_b32_e32 v17, v97
	v_mov_b32_e32 v18, v98
	v_mov_b32_e32 v19, v99
	v_mov_b32_e32 v12, v100
	v_mov_b32_e32 v13, v101
	v_mov_b32_e32 v14, v102
	v_mov_b32_e32 v15, v103
	v_mov_b32_e32 v32, v104
	v_mov_b32_e32 v33, v105
	v_mov_b32_e32 v34, v106
	v_mov_b32_e32 v35, v107
	v_mov_b32_e32 v28, v108
	v_mov_b32_e32 v29, v109
	v_mov_b32_e32 v30, v110
	v_mov_b32_e32 v31, v111
	v_pk_mul_f32 v[36:37], v[2:3], v[32:33]
	s_nop 0
	v_pk_fma_f32 v[36:37], v[20:21], v[16:17], v[36:37] neg_lo:[0,0,1] neg_hi:[0,0,1]
	v_pk_mul_f32 v[20:21], v[20:21], v[32:33]
	s_nop 0
	v_pk_fma_f32 v[2:3], v[2:3], v[16:17], v[20:21]
	v_pk_mul_f32 v[16:17], v[8:9], v[22:23] op_sel_hi:[0,1]
	v_pk_mul_f32 v[20:21], v[4:5], v[34:35]
	v_cvt_pk_bf16_f32 v0, v2, v3
	v_pk_fma_f32 v[20:21], v[16:17], v[18:19], v[20:21] neg_lo:[0,0,1] neg_hi:[0,0,1]
	v_pk_mul_f32 v[16:17], v[16:17], v[34:35]
	s_nop 0
	v_pk_fma_f32 v[4:5], v[4:5], v[18:19], v[16:17]
	ds_read_b128 v[16:19], v6 offset:80
	v_cvt_pk_bf16_f32 v1, v4, v5
	s_waitcnt lgkmcnt(0)
	v_pk_mul_f32 v[6:7], v[8:9], v[16:17] op_sel_hi:[0,1]
	v_pk_mul_f32 v[16:17], v[8:9], v[24:25] op_sel_hi:[0,1]
	v_pk_mul_f32 v[22:23], v[6:7], v[28:29]
	s_nop 0
	v_pk_fma_f32 v[22:23], v[16:17], v[12:13], v[22:23] neg_lo:[0,0,1] neg_hi:[0,0,1]
	v_pk_mul_f32 v[16:17], v[16:17], v[28:29]
	s_nop 0
	v_pk_fma_f32 v[6:7], v[6:7], v[12:13], v[16:17]
	v_pk_mul_f32 v[12:13], v[8:9], v[18:19] op_sel_hi:[0,1]
	v_pk_mul_f32 v[8:9], v[8:9], v[26:27] op_sel_hi:[0,1]
	v_pk_mul_f32 v[16:17], v[12:13], v[30:31]
	v_cvt_pk_bf16_f32 v2, v6, v7
	v_pk_fma_f32 v[16:17], v[8:9], v[14:15], v[16:17] neg_lo:[0,0,1] neg_hi:[0,0,1]
	v_pk_mul_f32 v[8:9], v[8:9], v[30:31]
	s_nop 0
	v_pk_fma_f32 v[8:9], v[12:13], v[14:15], v[8:9]
	v_cvt_pk_bf16_f32 v12, v36, v37
	v_cvt_pk_bf16_f32 v13, v20, v21
	v_cvt_pk_bf16_f32 v14, v22, v23
	v_cvt_pk_bf16_f32 v15, v16, v17
	v_cvt_pk_bf16_f32 v3, v8, v9
	global_store_dwordx4 v[10:11], v[12:15], off
	global_store_dwordx4 v[10:11], v[0:3], off offset:32
